# also ph_prep (12 row loads up front), ph_vat (8 loads together), ph_final (gain vector loaded once before the row loop)
# speedup vs baseline: 1.0453x; 1.0128x over previous
.LBB0_370:
	v_readlane_b32 s8, v253, 4
	s_cmp_le_i32 s8, s2
	s_cselect_b64 s[4:5], -1, 0
	s_and_b64 s[46:47], s[4:5], s[36:37]
	s_andn2_b64 vcc, exec, s[46:47]
	v_readlane_b32 s9, v253, 5
	v_readlane_b32 s10, v253, 6
	v_readlane_b32 s11, v253, 7
	s_cbranch_vccnz .LBB0_456
	v_readlane_b32 s4, v253, 0
	v_readlane_b32 s5, v253, 1
	s_load_dwordx2 s[38:39], s[4:5], 0x58
	s_waitcnt lgkmcnt(0)
	s_load_dwordx2 s[40:41], s[4:5], 0x50
	s_waitcnt lgkmcnt(0)
	s_lshl_b32 s2, s92, 3
	s_add_i32 s48, s2, s93
	s_cmpk_gt_i32 s48, 0x41ff
	v_mbcnt_lo_u32_b32 v0, -1, 0
	v_mbcnt_hi_u32_b32 v0, -1, v0
	s_cbranch_scc1 .LBB0_441
	s_waitcnt lgkmcnt(0)
	v_and_b32_e32 v1, 15, v0
	v_cvt_f32_ubyte0_e32 v1, v1
	v_mul_f32_e32 v1, 0xbd800000, v1
	v_cmp_eq_f32_e32 vcc, 0, v1
	v_mov_b32_e32 v2, 0x461c4000
	s_mov_b32 s2, 0x3f2aaaab
	s_waitcnt vmcnt(0)
	v_cndmask_b32_e64 v12, v2, 1.0, vcc
	v_frexp_mant_f32_e32 v2, v12
	v_cmp_gt_f32_e64 s[36:37], s2, v2
	s_mov_b32 s2, 0x3f317218
	v_readlane_b32 s4, v255, 7
	v_cndmask_b32_e64 v3, 1.0, 2.0, s[36:37]
	v_mul_f32_e32 v2, v2, v3
	v_add_f32_e32 v5, 1.0, v2
	v_rcp_f32_e32 v10, v5
	v_add_f32_e32 v3, -1.0, v5
	v_sub_f32_e32 v7, v2, v3
	v_add_f32_e32 v3, -1.0, v2
	v_mul_f32_e32 v11, v3, v10
	v_mul_f32_e32 v4, v5, v11
	v_fma_f32 v6, v11, v5, -v4
	v_fmac_f32_e32 v6, v11, v7
	v_add_f32_e32 v2, v4, v6
	v_sub_f32_e32 v5, v3, v2
	v_pk_add_f32 v[8:9], v[2:3], v[4:5] neg_lo:[0,1] neg_hi:[0,1]
	v_mov_b32_e32 v7, v2
	v_pk_add_f32 v[2:3], v[8:9], v[6:7] neg_lo:[0,1] neg_hi:[0,1]
	v_mov_b32_e32 v6, 0x3e91f4c4
	v_add_f32_e32 v2, v2, v3
	v_add_f32_e32 v2, v5, v2
	v_mul_f32_e32 v3, v10, v2
	v_add_f32_e32 v2, v11, v3
	v_sub_f32_e32 v4, v2, v11
	v_sub_f32_e32 v13, v3, v4
	v_mul_f32_e32 v3, v2, v2
	v_fma_f32 v5, v2, v2, -v3
	v_add_f32_e32 v4, v13, v13
	v_fmac_f32_e32 v5, v2, v4
	v_add_f32_e32 v4, v3, v5
	v_fmamk_f32 v6, v4, 0x3e76c4e1, v6
	v_fmaak_f32 v6, v4, v6, 0x3ecccdef
	v_sub_f32_e32 v3, v4, v3
	v_sub_f32_e32 v14, v5, v3
	v_mul_f32_e32 v3, v4, v6
	v_fma_f32 v5, v4, v6, -v3
	v_fmac_f32_e32 v5, v14, v6
	v_add_f32_e32 v6, v3, v5
	v_add_f32_e32 v7, 0x3f2aaaaa, v6
	v_sub_f32_e32 v3, v6, v3
	v_sub_f32_e32 v3, v5, v3
	v_add_f32_e32 v5, 0xbf2aaaaa, v7
	v_add_f32_e32 v3, 0x31739010, v3
	v_sub_f32_e32 v5, v6, v5
	v_pk_mul_f32 v[8:9], v[2:3], v[4:5]
	v_pk_add_f32 v[10:11], v[2:3], v[4:5]
	v_fma_f32 v6, v4, v2, -v8
	v_fmac_f32_e32 v6, v4, v13
	v_mov_b32_e32 v9, v11
	v_fmac_f32_e32 v6, v14, v2
	v_pk_add_f32 v[4:5], v[8:9], v[6:7]
	v_ldexp_f32 v14, v13, 1
	v_sub_f32_e32 v3, v4, v8
	v_sub_f32_e32 v3, v6, v3
	v_sub_f32_e32 v6, v7, v5
	v_add_f32_e32 v10, v11, v6
	v_pk_mul_f32 v[6:7], v[4:5], v[4:5] op_sel:[0,1] op_sel_hi:[1,0]
	v_cvt_f64_f32_e32 v[8:9], v12
	v_frexp_exp_i32_f64_e32 v7, v[8:9]
	v_subbrev_co_u32_e64 v7, s[36:37], 0, v7, s[36:37]
	v_cvt_f32_i32_e32 v7, v7
	v_fma_f32 v8, v4, v5, -v6
	v_fmac_f32_e32 v8, v4, v10
	v_fmac_f32_e32 v8, v3, v5
	v_mul_f32_e32 v4, 0x3f317218, v7
	v_fma_f32 v10, v7, s2, -v4
	v_fmac_f32_e32 v10, 0xb102e308, v7
	v_ldexp_f32 v11, v2, 1
	v_add_f32_e32 v5, v6, v8
	v_pk_add_f32 v[2:3], v[4:5], v[10:11]
	v_mov_b32_e32 v12, v5
	v_mov_b32_e32 v13, v3
	v_mov_b32_e32 v7, v11
	v_pk_add_f32 v[6:7], v[12:13], v[6:7] neg_lo:[0,1] neg_hi:[0,1]
	v_mov_b32_e32 v9, v5
	v_pk_add_f32 v[6:7], v[8:9], v[6:7] neg_lo:[0,1] neg_hi:[0,1]
	v_mov_b32_e32 v11, v2
	v_add_f32_e32 v5, v14, v6
	v_add_f32_e32 v5, v5, v7
	v_pk_add_f32 v[6:7], v[2:3], v[4:5] neg_lo:[0,1] neg_hi:[0,1]
	v_pk_add_f32 v[8:9], v[2:3], v[4:5]
	v_mov_b32_e32 v4, v5
	v_mov_b32_e32 v7, v9
	v_pk_add_f32 v[12:13], v[10:11], v[6:7] neg_lo:[0,1] neg_hi:[0,1]
	v_pk_add_f32 v[6:7], v[10:11], v[6:7]
	v_mov_b32_e32 v5, v2
	v_pk_add_f32 v[10:11], v[6:7], v[2:3] op_sel:[1,0] op_sel_hi:[0,1] neg_lo:[0,1] neg_hi:[0,1]
	v_pk_add_f32 v[14:15], v[8:9], v[10:11] op_sel_hi:[1,0] neg_lo:[0,1] neg_hi:[0,1]
	v_mov_b32_e32 v8, v9
	v_mov_b32_e32 v9, v7
	v_pk_mov_b32 v[10:11], v[2:3], v[10:11] op_sel:[1,0]
	v_mov_b32_e32 v14, v12
	v_pk_add_f32 v[8:9], v[8:9], v[10:11] neg_lo:[0,1] neg_hi:[0,1]
	v_lshl_add_u32 v10, s4, 6, v0
	v_ashrrev_i32_e32 v11, 31, v10
	v_pk_add_f32 v[2:3], v[4:5], v[8:9] neg_lo:[0,1] neg_hi:[0,1]
	v_lshlrev_b64 v[10:11], 2, v[10:11]
	v_pk_add_f32 v[4:5], v[14:15], v[2:3]
	v_lshl_add_u64 v[14:15], s[38:39], 0, v[10:11]
	v_lshl_add_u64 v[10:11], s[40:41], 0, v[10:11]
	global_load_dword v16, v[14:15], off
	global_load_dword v17, v[10:11], off
	v_pk_add_f32 v[8:9], v[4:5], v[4:5] op_sel:[0,1] op_sel_hi:[1,0]
	v_mov_b32_e32 v13, v7
	v_pk_add_f32 v[6:7], v[6:7], v[8:9] op_sel:[1,0] op_sel_hi:[0,1]
	v_mov_b32_e32 v5, v6
	v_pk_add_f32 v[10:11], v[4:5], v[12:13] neg_lo:[0,1] neg_hi:[0,1]
	v_mov_b32_e32 v3, v8
	v_sub_f32_e32 v4, v4, v10
	v_pk_add_f32 v[2:3], v[2:3], v[10:11] neg_lo:[0,1] neg_hi:[0,1]
	v_sub_f32_e32 v4, v12, v4
	v_add_f32_e32 v2, v2, v4
	v_add_f32_e32 v2, v2, v3
	v_add_f32_e32 v3, v6, v2
	v_sub_f32_e32 v4, v3, v6
	v_sub_f32_e32 v2, v2, v4
	v_mul_f32_e32 v4, v1, v3
	v_fma_f32 v3, v1, v3, -v4
	v_fmac_f32_e32 v3, v1, v2
	s_movk_i32 s6, 0x204
	v_add_f32_e32 v2, v4, v3
	v_cmp_class_f32_e64 s[36:37], v4, s6
	v_sub_f32_e32 v5, v2, v4
	s_mov_b32 s4, 0x42b17218
	v_cndmask_b32_e64 v2, v2, v4, s[36:37]
	v_cmp_eq_f32_e64 s[36:37], s4, v2
	v_mov_b32_e32 v4, 0x37000000
	v_sub_f32_e32 v3, v3, v5
	v_cndmask_b32_e64 v4, 0, v4, s[36:37]
	v_sub_f32_e32 v5, v2, v4
	v_mul_f32_e32 v6, 0x3fb8aa3b, v5
	v_fma_f32 v7, v5, s1, -v6
	v_rndne_f32_e32 v8, v6
	v_fmac_f32_e32 v7, 0x32a5705f, v5
	v_sub_f32_e32 v6, v6, v8
	v_add_f32_e32 v6, v6, v7
	v_exp_f32_e32 v6, v6
	v_cvt_i32_f32_e32 v7, v8
	s_mov_b32 s2, 0x7f800000
	v_cmp_neq_f32_e64 s[36:37], |v2|, s2
	s_mov_b32 s2, 0xc2ce8ed0
	v_readlane_b32 s5, v255, 8
	v_cndmask_b32_e64 v2, 0, v3, s[36:37]
	v_ldexp_f32 v3, v6, v7
	v_cmp_ngt_f32_e64 s[36:37], s2, v5
	v_add_f32_e32 v2, v4, v2
	v_mov_b32_e32 v4, 0x7f800000
	v_cndmask_b32_e64 v3, 0, v3, s[36:37]
	v_cmp_nlt_f32_e64 s[36:37], s4, v5
	v_cmp_neq_f32_e64 s[4:5], v1, |v1|
	s_lshl_b32 s50, s77, 3
	v_cndmask_b32_e64 v3, v4, v3, s[36:37]
	v_fma_f32 v2, v3, v2, v3
	v_cmp_class_f32_e64 s[36:37], v3, s6
	s_ashr_i32 s49, s48, 31
	s_ashr_i32 s51, s50, 31
	v_cndmask_b32_e64 v2, v2, v3, s[36:37]
	v_cndmask_b32_e64 v3, v4, 0, s[4:5]
	v_cndmask_b32_e64 v3, v3, 1.0, vcc
	v_cmp_class_f32_e64 s[4:5], v1, s6
	v_xor_b32_e32 v1, 16, v239
	s_lshl_b64 s[52:53], s[50:51], 10
	v_cndmask_b32_e64 v18, |v2|, v3, s[4:5]
	v_and_b32_e32 v2, 64, v239
	v_add_u32_e32 v2, 64, v2
	v_cmp_lt_i32_e32 vcc, v1, v2
	s_mov_b64 s[4:5], 0x2e800000
	v_add_u32_e32 v8, 0x880, v0
	v_cndmask_b32_e32 v1, v239, v1, vcc
	v_lshlrev_b32_e32 v19, 2, v1
	v_and_b32_e32 v1, 16, v0
	v_cmp_ne_u32_e64 s[38:39], 0, v1
	v_ashrrev_i32_e32 v1, 31, v0
	v_lshlrev_b64 v[10:11], 1, v[0:1]
	v_lshl_add_u64 v[2:3], s[74:75], 0, v[10:11]
	v_lshl_add_u64 v[2:3], v[2:3], 0, s[4:5]
	s_lshl_b64 s[4:5], s[48:49], 10
	v_lshl_add_u64 v[4:5], s[4:5], 0, v[10:11]
	s_mul_i32 s4, s48, 0x2e00
	v_add_u32_e32 v6, 0x8c0, v0
	s_mul_hi_i32 s2, s48, 0x2e00
	s_add_u32 s4, s4, 0x21400000
	v_ashrrev_i32_e32 v9, 31, v8
	v_ashrrev_i32_e32 v7, 31, v6
	s_addc_u32 s5, s2, 0
	v_mov_b32_e32 v12, 0x2e00
	v_cmp_gt_u32_e64 s[36:37], 32, v0
	v_lshl_add_u64 v[6:7], v[6:7], 1, s[4:5]
	s_mul_i32 s54, s77, 0x17000
	s_mul_hi_i32 s55, s50, 0x2e00
	v_lshl_add_u64 v[8:9], v[8:9], 1, s[4:5]
	v_mad_i64_i32 v[10:11], s[4:5], s48, v12, v[10:11]
	v_mbcnt_lo_u32_b32 v231, -1, 0
	v_mbcnt_hi_u32_b32 v231, -1, v231
	v_lshlrev_b32_e32 v231, 1, v231
	v_add_u32_e32 v231, 0x21400c00, v231
	s_branch .LBB0_375

.LBB0_374:
	s_waitcnt lgkmcnt(0)
	v_bfe_u32 v13, v12, 16, 1
	v_add3_u32 v20, v12, v13, s3
	v_add_co_u32_e32 v12, vcc, 0x2e300000, v14
	s_lshl_b64 s[4:5], s[44:45], 7
	s_nop 0
	v_addc_co_u32_e32 v13, vcc, 0, v15, vcc
	global_store_short_d16_hi v[12:13], v20, off offset:128
	v_lshl_add_u64 v[12:13], s[74:75], 0, v[8:9]
	s_waitcnt vmcnt(11)
	v_mov_b32_e32 v20, v250
	v_lshl_add_u64 v[14:15], s[4:5], 1, v[2:3]
	v_lshl_add_u64 v[12:13], s[74:75], 0, v[6:7]
	s_add_i32 s48, s48, s50
	v_lshl_add_u64 v[4:5], v[4:5], 0, s[52:53]
	v_lshl_add_u64 v[6:7], v[6:7], 0, s[54:55]
	v_lshl_add_u64 v[8:9], v[8:9], 0, s[54:55]
	s_cmpk_lt_i32 s48, 0x4200
	v_lshl_add_u64 v[10:11], v[10:11], 0, s[54:55]
	global_store_short v[14:15], v20, off
	s_waitcnt vmcnt(11)
	v_mov_b32_e32 v12, v251
	global_store_short v[14:15], v12, off offset:128
	s_cbranch_scc0 .LBB0_441
.LBB0_375:
	s_mul_i32 s2, s48, 0x2e00
	v_add_u32_e32 v232, s2, v231
	global_load_ushort v240, v232, s[74:75]
	global_load_ushort v241, v232, s[74:75] offset:128
	global_load_ushort v242, v232, s[74:75] offset:256
	global_load_ushort v243, v232, s[74:75] offset:384
	global_load_ushort v244, v232, s[74:75] offset:512
	global_load_ushort v245, v232, s[74:75] offset:640
	global_load_ushort v246, v232, s[74:75] offset:768
	global_load_ushort v247, v232, s[74:75] offset:896
	global_load_ushort v248, v232, s[74:75] offset:1024
	global_load_ushort v249, v232, s[74:75] offset:1152
	global_load_ushort v250, v232, s[74:75] offset:1280
	global_load_ushort v251, v232, s[74:75] offset:1408
	s_cmpk_lt_i32 s48, 0x4000
	s_cselect_b64 s[56:57], -1, 0
	s_and_b64 s[4:5], s[56:57], exec
	s_movk_i32 s2, 0x1fff
	s_cselect_b32 s2, s2, 0xff
	s_and_b32 s2, s2, s48
	s_cmpk_gt_i32 s48, 0x3fff
	s_cbranch_scc1 .LBB0_381
	s_lshr_b32 s4, s2, 6
	s_and_b32 s5, s48, 63
	v_mov_b32_e32 v12, s5
	v_mov_b32_e32 v13, s4
	v_cndmask_b32_e64 v12, v12, v13, s[36:37]
	v_cvt_f32_ubyte0_e32 v12, v12
	v_mul_f32_e32 v12, v18, v12
	s_brev_b32 s4, 18
	v_and_b32_e32 v13, 0x7fffffff, v12
	v_cmp_nlt_f32_e64 s[4:5], |v12|, s4
	s_and_saveexec_b64 s[8:9], s[4:5]
	s_xor_b64 s[58:59], exec, s[8:9]
	s_cbranch_execz .LBB0_378
	v_lshrrev_b32_e32 v14, 23, v13
	v_add_u32_e32 v14, 0xffffff88, v14
	v_cmp_lt_u32_e32 vcc, 63, v14
	v_not_b32_e32 v15, 63
	v_not_b32_e32 v20, 31
	v_cndmask_b32_e32 v15, 0, v15, vcc
	v_add_u32_e32 v14, v15, v14
	v_cmp_lt_u32_e64 s[40:41], 31, v14
	s_mov_b32 s4, 0xfe5163ab
	s_nop 0
	v_cndmask_b32_e64 v15, 0, v20, s[40:41]
	v_add_u32_e32 v14, v15, v14
	v_cmp_lt_u32_e64 s[42:43], 31, v14
	s_nop 1
	v_cndmask_b32_e64 v15, 0, v20, s[42:43]
	v_add_u32_e32 v32, v15, v14
	v_and_b32_e32 v14, 0x7fffff, v13
	v_or_b32_e32 v30, 0x800000, v14
	v_mad_u64_u32 v[14:15], s[4:5], v30, s4, 0
	v_mov_b32_e32 v208, v15
	s_mov_b32 s4, 0x3c439041
	v_mad_u64_u32 v[20:21], s[4:5], v30, s4, v[208:209]
	v_mov_b32_e32 v208, v21
	s_mov_b32 s4, 0xdb629599
	v_mad_u64_u32 v[22:23], s[4:5], v30, s4, v[208:209]
	v_mov_b32_e32 v208, v23
	s_mov_b32 s4, 0xf534ddc0
	v_mad_u64_u32 v[24:25], s[4:5], v30, s4, v[208:209]
	v_mov_b32_e32 v208, v25
	s_mov_b32 s4, 0xfc2757d1
	v_mad_u64_u32 v[26:27], s[4:5], v30, s4, v[208:209]
	v_mov_b32_e32 v208, v27
	s_mov_b32 s4, 0x4e441529
	v_mad_u64_u32 v[28:29], s[4:5], v30, s4, v[208:209]
	v_mov_b32_e32 v208, v29
	s_mov_b32 s4, 0xa2f9836e
	v_mad_u64_u32 v[30:31], s[4:5], v30, s4, v[208:209]
	v_cndmask_b32_e32 v15, v28, v24, vcc
	v_cndmask_b32_e32 v21, v30, v26, vcc
	v_cndmask_b32_e32 v25, v31, v28, vcc
	v_cndmask_b32_e64 v23, v21, v15, s[40:41]
	v_cndmask_b32_e64 v21, v25, v21, s[40:41]
	v_cndmask_b32_e32 v25, v26, v22, vcc
	v_cndmask_b32_e64 v15, v15, v25, s[40:41]
	v_cndmask_b32_e32 v20, v24, v20, vcc
	v_cndmask_b32_e64 v21, v21, v23, s[42:43]
	v_cndmask_b32_e64 v23, v23, v15, s[42:43]
	v_sub_u32_e32 v26, 32, v32
	v_cndmask_b32_e64 v24, v25, v20, s[40:41]
	v_alignbit_b32 v27, v21, v23, v26
	v_cmp_eq_u32_e64 s[44:45], 0, v32
	v_cndmask_b32_e64 v15, v15, v24, s[42:43]
	v_alignbit_b32 v25, v23, v15, v26
	v_cndmask_b32_e64 v21, v27, v21, s[44:45]
	v_cndmask_b32_e32 v14, v22, v14, vcc
	v_cndmask_b32_e64 v23, v25, v23, s[44:45]
	v_bfe_u32 v28, v21, 29, 1
	v_cndmask_b32_e64 v14, v20, v14, s[40:41]
	v_alignbit_b32 v25, v21, v23, 30
	v_sub_u32_e32 v29, 0, v28
	v_cndmask_b32_e64 v14, v24, v14, s[42:43]
	v_xor_b32_e32 v25, v25, v29
	v_alignbit_b32 v20, v15, v14, v26
	v_cndmask_b32_e64 v15, v20, v15, s[44:45]
	v_ffbh_u32_e32 v22, v25
	v_alignbit_b32 v20, v23, v15, 30
	v_min_u32_e32 v22, 32, v22
	v_alignbit_b32 v14, v15, v14, 30
	v_xor_b32_e32 v20, v20, v29
	v_sub_u32_e32 v23, 31, v22
	v_xor_b32_e32 v14, v14, v29
	v_alignbit_b32 v24, v25, v20, v23
	v_alignbit_b32 v14, v20, v14, v23
	v_alignbit_b32 v15, v24, v14, 9
	v_ffbh_u32_e32 v20, v15
	v_min_u32_e32 v20, 32, v20
	v_lshrrev_b32_e32 v27, 29, v21
	v_not_b32_e32 v23, v20
	v_alignbit_b32 v14, v15, v14, v23
	v_lshlrev_b32_e32 v15, 31, v27
	v_or_b32_e32 v23, 0x33000000, v15
	v_add_lshl_u32 v20, v20, v22, 23
	v_lshrrev_b32_e32 v14, 9, v14
	v_sub_u32_e32 v20, v23, v20
	v_or_b32_e32 v15, 0.5, v15
	v_lshlrev_b32_e32 v22, 23, v22
	v_or_b32_e32 v14, v20, v14
	v_lshrrev_b32_e32 v20, 9, v24
	v_sub_u32_e32 v15, v15, v22
	v_or_b32_e32 v15, v20, v15
	v_mul_f32_e32 v20, 0x3fc90fda, v15
	s_mov_b32 s4, 0x3fc90fda
	v_fma_f32 v22, v15, s4, -v20
	v_fmac_f32_e32 v22, 0x33a22168, v15
	v_fmac_f32_e32 v22, 0x3fc90fda, v14
	v_lshrrev_b32_e32 v15, 30, v21
	v_add_f32_e32 v14, v20, v22
	v_add_u32_e32 v15, v28, v15

.LBB0_382:
	v_lshl_add_u64 v[12:13], s[74:75], 0, v[10:11]
	v_add_co_u32_e32 v14, vcc, 0x21400000, v12
	s_nop 1
	v_addc_co_u32_e32 v15, vcc, 0, v13, vcc
	s_waitcnt vmcnt(11)
	v_mov_b32_e32 v14, v240
	v_lshlrev_b32_e32 v22, 16, v14
	v_mul_f32_e32 v14, v22, v22
	s_nop 1
	v_mov_b32_dpp v14, v14 quad_perm:[1,0,3,2] row_mask:0xf bank_mask:0xf bound_ctrl:1
	v_fmac_f32_e32 v14, v22, v22
	s_nop 1
	v_add_f32_dpp v14, v14, v14 quad_perm:[2,3,0,1] row_mask:0xf bank_mask:0xf bound_ctrl:1
	s_nop 1
	v_add_f32_dpp v14, v14, v14 row_half_mirror row_mask:0xf bank_mask:0xf bound_ctrl:1
	s_nop 1
	v_add_f32_dpp v14, v14, v14 row_mirror row_mask:0xf bank_mask:0xf bound_ctrl:1
	s_nop 0
	v_readlane_b32 s6, v14, 16
	v_readlane_b32 s8, v14, 48
	v_readlane_b32 s4, v14, 0
	v_readlane_b32 s5, v14, 32
	v_mov_b32_e32 v14, s6
	v_mov_b32_e32 v15, s8
	v_pk_add_f32 v[14:15], s[4:5], v[14:15]
	s_mov_b32 s4, 0xf800000
	v_add_f32_e32 v14, v14, v15
	v_fmamk_f32 v14, v14, 0x3c800000, v252
	v_mul_f32_e32 v15, 0x4f800000, v14
	v_cmp_gt_f32_e32 vcc, s4, v14
	s_nop 1
	v_cndmask_b32_e32 v14, v14, v15, vcc
	v_sqrt_f32_e32 v15, v14
	s_nop 0
	v_add_u32_e32 v23, -1, v15
	v_add_u32_e32 v24, 1, v15
	v_fma_f32 v25, -v23, v15, v14
	v_fma_f32 v26, -v24, v15, v14
	v_cmp_ge_f32_e64 s[40:41], 0, v25
	s_nop 1
	v_cndmask_b32_e64 v15, v15, v23, s[40:41]
	v_cmp_lt_f32_e64 s[40:41], 0, v26
	s_nop 1
	v_cndmask_b32_e64 v15, v15, v24, s[40:41]
	v_mul_f32_e32 v23, 0x37800000, v15
	v_cndmask_b32_e32 v15, v15, v23, vcc
	v_mov_b32_e32 v23, 0x260
	v_cmp_class_f32_e32 vcc, v14, v23
	s_nop 1
	v_cndmask_b32_e32 v14, v15, v14, vcc
	v_div_scale_f32 v15, s[4:5], v14, v14, 1.0
	v_rcp_f32_e32 v23, v15
	v_div_scale_f32 v24, vcc, 1.0, v14, 1.0
	v_fma_f32 v25, -v15, v23, 1.0
	v_fmac_f32_e32 v23, v25, v23
	v_mul_f32_e32 v25, v24, v23
	v_fma_f32 v26, -v15, v25, v24
	v_fmac_f32_e32 v25, v26, v23
	v_fma_f32 v15, -v15, v25, v24
	v_div_fmas_f32 v15, v15, v23, v25
	v_div_fixup_f32 v14, v15, v14, 1.0
	v_mul_f32_e32 v14, v14, v22
	v_mul_f32_e32 v22, v17, v14
	ds_bpermute_b32 v14, v19, v22
	v_cndmask_b32_e64 v15, 0, 1, s[56:57]
	v_cmp_ne_u32_e64 s[40:41], 1, v15
	s_andn2_b64 vcc, exec, s[56:57]
	s_cbranch_vccnz .LBB0_388
	s_and_saveexec_b64 s[4:5], s[38:39]
	s_xor_b64 s[42:43], exec, s[4:5]
	s_cbranch_execz .LBB0_385
	v_mul_f32_e32 v22, v21, v22
	s_waitcnt lgkmcnt(0)
	v_fmac_f32_e32 v22, v20, v14

.LBB0_388:
	v_mul_f32_e32 v22, 0x3e38aa3b, v22
	s_waitcnt lgkmcnt(0)
	v_lshl_add_u64 v[14:15], s[74:75], 0, v[4:5]
	v_bfe_u32 v23, v22, 16, 1
	v_add3_u32 v24, v22, v23, s3
	v_add_co_u32_e32 v22, vcc, 0x2d200000, v14
	s_nop 1
	v_addc_co_u32_e32 v23, vcc, 0, v15, vcc
	global_store_short_d16_hi v[22:23], v24, off
	v_add_co_u32_e32 v22, vcc, 0x21400000, v12
	s_nop 1
	v_addc_co_u32_e32 v23, vcc, 0, v13, vcc
	s_waitcnt vmcnt(11)
	v_mov_b32_e32 v22, v241
	v_lshlrev_b32_e32 v24, 16, v22
	v_mul_f32_e32 v22, v24, v24
	s_nop 1
	v_mov_b32_dpp v22, v22 quad_perm:[1,0,3,2] row_mask:0xf bank_mask:0xf bound_ctrl:1
	v_fmac_f32_e32 v22, v24, v24
	s_nop 1
	v_add_f32_dpp v22, v22, v22 quad_perm:[2,3,0,1] row_mask:0xf bank_mask:0xf bound_ctrl:1
	s_nop 1
	v_add_f32_dpp v22, v22, v22 row_half_mirror row_mask:0xf bank_mask:0xf bound_ctrl:1
	s_nop 1
	v_add_f32_dpp v22, v22, v22 row_mirror row_mask:0xf bank_mask:0xf bound_ctrl:1
	s_nop 0
	v_readlane_b32 s6, v22, 16
	v_readlane_b32 s8, v22, 48
	v_readlane_b32 s4, v22, 0
	v_readlane_b32 s5, v22, 32
	v_mov_b32_e32 v22, s6
	v_mov_b32_e32 v23, s8
	v_pk_add_f32 v[22:23], s[4:5], v[22:23]
	s_mov_b32 s4, 0xf800000
	v_add_f32_e32 v22, v22, v23
	v_fmamk_f32 v22, v22, 0x3c800000, v252
	v_mul_f32_e32 v23, 0x4f800000, v22
	v_cmp_gt_f32_e32 vcc, s4, v22
	s_nop 1
	v_cndmask_b32_e32 v22, v22, v23, vcc
	v_sqrt_f32_e32 v23, v22
	s_nop 0
	v_add_u32_e32 v25, -1, v23
	v_add_u32_e32 v26, 1, v23
	v_fma_f32 v27, -v25, v23, v22
	v_fma_f32 v28, -v26, v23, v22
	v_cmp_ge_f32_e64 s[42:43], 0, v27
	s_nop 1
	v_cndmask_b32_e64 v23, v23, v25, s[42:43]
	v_cmp_lt_f32_e64 s[42:43], 0, v28
	s_nop 1
	v_cndmask_b32_e64 v23, v23, v26, s[42:43]
	v_mul_f32_e32 v25, 0x37800000, v23
	v_cndmask_b32_e32 v23, v23, v25, vcc
	v_mov_b32_e32 v25, 0x260
	v_cmp_class_f32_e32 vcc, v22, v25
	s_nop 1
	v_cndmask_b32_e32 v22, v23, v22, vcc
	v_div_scale_f32 v23, s[4:5], v22, v22, 1.0
	v_rcp_f32_e32 v25, v23
	v_div_scale_f32 v26, vcc, 1.0, v22, 1.0
	v_fma_f32 v27, -v23, v25, 1.0
	v_fmac_f32_e32 v25, v27, v25
	v_mul_f32_e32 v27, v26, v25
	v_fma_f32 v28, -v23, v27, v26
	v_fmac_f32_e32 v27, v28, v25
	v_fma_f32 v23, -v23, v27, v26
	v_div_fmas_f32 v23, v23, v25, v27
	v_div_fixup_f32 v22, v23, v22, 1.0
	v_mul_f32_e32 v22, v22, v24
	v_mul_f32_e32 v22, v17, v22
	ds_bpermute_b32 v23, v19, v22
	s_and_b64 vcc, exec, s[40:41]
	s_cbranch_vccnz .LBB0_394
	s_and_saveexec_b64 s[4:5], s[38:39]
	s_xor_b64 s[42:43], exec, s[4:5]
	s_cbranch_execz .LBB0_391
	v_mul_f32_e32 v22, v21, v22
	s_waitcnt lgkmcnt(0)
	v_fmac_f32_e32 v22, v20, v23

.LBB0_394:
	v_mul_f32_e32 v22, 0x3e38aa3b, v22
	s_waitcnt lgkmcnt(0)
	v_bfe_u32 v23, v22, 16, 1
	v_add3_u32 v24, v22, v23, s3
	v_add_co_u32_e32 v22, vcc, 0x2d200000, v14
	s_nop 1
	v_addc_co_u32_e32 v23, vcc, 0, v15, vcc
	global_store_short_d16_hi v[22:23], v24, off offset:128
	v_add_co_u32_e32 v22, vcc, 0x21400000, v12
	s_nop 1
	v_addc_co_u32_e32 v23, vcc, 0, v13, vcc
	s_waitcnt vmcnt(11)
	v_mov_b32_e32 v22, v242
	v_lshlrev_b32_e32 v24, 16, v22
	v_mul_f32_e32 v22, v24, v24
	s_nop 1
	v_mov_b32_dpp v22, v22 quad_perm:[1,0,3,2] row_mask:0xf bank_mask:0xf bound_ctrl:1
	v_fmac_f32_e32 v22, v24, v24
	s_nop 1
	v_add_f32_dpp v22, v22, v22 quad_perm:[2,3,0,1] row_mask:0xf bank_mask:0xf bound_ctrl:1
	s_nop 1
	v_add_f32_dpp v22, v22, v22 row_half_mirror row_mask:0xf bank_mask:0xf bound_ctrl:1
	s_nop 1
	v_add_f32_dpp v22, v22, v22 row_mirror row_mask:0xf bank_mask:0xf bound_ctrl:1
	s_nop 0
	v_readlane_b32 s6, v22, 16
	v_readlane_b32 s8, v22, 48
	v_readlane_b32 s4, v22, 0
	v_readlane_b32 s5, v22, 32
	v_mov_b32_e32 v22, s6
	v_mov_b32_e32 v23, s8
	v_pk_add_f32 v[22:23], s[4:5], v[22:23]
	s_mov_b32 s4, 0xf800000
	v_add_f32_e32 v22, v22, v23
	v_fmamk_f32 v22, v22, 0x3c800000, v252
	v_mul_f32_e32 v23, 0x4f800000, v22
	v_cmp_gt_f32_e32 vcc, s4, v22
	s_nop 1
	v_cndmask_b32_e32 v22, v22, v23, vcc
	v_sqrt_f32_e32 v23, v22
	s_nop 0
	v_add_u32_e32 v25, -1, v23
	v_add_u32_e32 v26, 1, v23
	v_fma_f32 v27, -v25, v23, v22
	v_fma_f32 v28, -v26, v23, v22
	v_cmp_ge_f32_e64 s[42:43], 0, v27
	s_nop 1
	v_cndmask_b32_e64 v23, v23, v25, s[42:43]
	v_cmp_lt_f32_e64 s[42:43], 0, v28
	s_nop 1
	v_cndmask_b32_e64 v23, v23, v26, s[42:43]
	v_mul_f32_e32 v25, 0x37800000, v23
	v_cndmask_b32_e32 v23, v23, v25, vcc
	v_mov_b32_e32 v25, 0x260
	v_cmp_class_f32_e32 vcc, v22, v25
	s_nop 1
	v_cndmask_b32_e32 v22, v23, v22, vcc
	v_div_scale_f32 v23, s[4:5], v22, v22, 1.0
	v_rcp_f32_e32 v25, v23
	v_div_scale_f32 v26, vcc, 1.0, v22, 1.0
	v_fma_f32 v27, -v23, v25, 1.0
	v_fmac_f32_e32 v25, v27, v25
	v_mul_f32_e32 v27, v26, v25
	v_fma_f32 v28, -v23, v27, v26
	v_fmac_f32_e32 v27, v28, v25
	v_fma_f32 v23, -v23, v27, v26
	v_div_fmas_f32 v23, v23, v25, v27
	v_div_fixup_f32 v22, v23, v22, 1.0
	v_mul_f32_e32 v22, v22, v24
	v_mul_f32_e32 v22, v17, v22
	ds_bpermute_b32 v23, v19, v22
	s_and_b64 vcc, exec, s[40:41]
	s_cbranch_vccnz .LBB0_400
	s_and_saveexec_b64 s[4:5], s[38:39]
	s_xor_b64 s[42:43], exec, s[4:5]
	s_cbranch_execz .LBB0_397
	v_mul_f32_e32 v22, v21, v22
	s_waitcnt lgkmcnt(0)
	v_fmac_f32_e32 v22, v20, v23

.LBB0_400:
	v_mul_f32_e32 v22, 0x3e38aa3b, v22
	s_waitcnt lgkmcnt(0)
	v_bfe_u32 v23, v22, 16, 1
	v_add3_u32 v24, v22, v23, s3
	v_add_co_u32_e32 v22, vcc, 0x2d200000, v14
	s_nop 1
	v_addc_co_u32_e32 v23, vcc, 0, v15, vcc
	global_store_short_d16_hi v[22:23], v24, off offset:256
	v_add_co_u32_e32 v22, vcc, 0x21400000, v12
	s_nop 1
	v_addc_co_u32_e32 v23, vcc, 0, v13, vcc
	s_waitcnt vmcnt(11)
	v_mov_b32_e32 v22, v243
	v_lshlrev_b32_e32 v24, 16, v22
	v_mul_f32_e32 v22, v24, v24
	s_nop 1
	v_mov_b32_dpp v22, v22 quad_perm:[1,0,3,2] row_mask:0xf bank_mask:0xf bound_ctrl:1
	v_fmac_f32_e32 v22, v24, v24
	s_nop 1
	v_add_f32_dpp v22, v22, v22 quad_perm:[2,3,0,1] row_mask:0xf bank_mask:0xf bound_ctrl:1
	s_nop 1
	v_add_f32_dpp v22, v22, v22 row_half_mirror row_mask:0xf bank_mask:0xf bound_ctrl:1
	s_nop 1
	v_add_f32_dpp v22, v22, v22 row_mirror row_mask:0xf bank_mask:0xf bound_ctrl:1
	s_nop 0
	v_readlane_b32 s6, v22, 16
	v_readlane_b32 s8, v22, 48
	v_readlane_b32 s4, v22, 0
	v_readlane_b32 s5, v22, 32
	v_mov_b32_e32 v22, s6
	v_mov_b32_e32 v23, s8
	v_pk_add_f32 v[22:23], s[4:5], v[22:23]
	s_mov_b32 s4, 0xf800000
	v_add_f32_e32 v22, v22, v23
	v_fmamk_f32 v22, v22, 0x3c800000, v252
	v_mul_f32_e32 v23, 0x4f800000, v22
	v_cmp_gt_f32_e32 vcc, s4, v22
	s_nop 1
	v_cndmask_b32_e32 v22, v22, v23, vcc
	v_sqrt_f32_e32 v23, v22
	s_nop 0
	v_add_u32_e32 v25, -1, v23
	v_add_u32_e32 v26, 1, v23
	v_fma_f32 v27, -v25, v23, v22
	v_fma_f32 v28, -v26, v23, v22
	v_cmp_ge_f32_e64 s[42:43], 0, v27
	s_nop 1
	v_cndmask_b32_e64 v23, v23, v25, s[42:43]
	v_cmp_lt_f32_e64 s[42:43], 0, v28
	s_nop 1
	v_cndmask_b32_e64 v23, v23, v26, s[42:43]
	v_mul_f32_e32 v25, 0x37800000, v23
	v_cndmask_b32_e32 v23, v23, v25, vcc
	v_mov_b32_e32 v25, 0x260
	v_cmp_class_f32_e32 vcc, v22, v25
	s_nop 1
	v_cndmask_b32_e32 v22, v23, v22, vcc
	v_div_scale_f32 v23, s[4:5], v22, v22, 1.0
	v_rcp_f32_e32 v25, v23
	v_div_scale_f32 v26, vcc, 1.0, v22, 1.0
	v_fma_f32 v27, -v23, v25, 1.0
	v_fmac_f32_e32 v25, v27, v25
	v_mul_f32_e32 v27, v26, v25
	v_fma_f32 v28, -v23, v27, v26
	v_fmac_f32_e32 v27, v28, v25
	v_fma_f32 v23, -v23, v27, v26
	v_div_fmas_f32 v23, v23, v25, v27
	v_div_fixup_f32 v22, v23, v22, 1.0
	v_mul_f32_e32 v22, v22, v24
	v_mul_f32_e32 v22, v17, v22
	ds_bpermute_b32 v23, v19, v22
	s_and_b64 vcc, exec, s[40:41]
	s_cbranch_vccnz .LBB0_406
	s_and_saveexec_b64 s[4:5], s[38:39]
	s_xor_b64 s[42:43], exec, s[4:5]
	s_cbranch_execz .LBB0_403
	v_mul_f32_e32 v22, v21, v22
	s_waitcnt lgkmcnt(0)
	v_fmac_f32_e32 v22, v20, v23

.LBB0_406:
	v_mul_f32_e32 v22, 0x3e38aa3b, v22
	s_waitcnt lgkmcnt(0)
	v_bfe_u32 v23, v22, 16, 1
	v_add3_u32 v24, v22, v23, s3
	v_add_co_u32_e32 v22, vcc, 0x2d200000, v14
	s_nop 1
	v_addc_co_u32_e32 v23, vcc, 0, v15, vcc
	global_store_short_d16_hi v[22:23], v24, off offset:384
	v_add_co_u32_e32 v22, vcc, 0x21400000, v12
	s_nop 1
	v_addc_co_u32_e32 v23, vcc, 0, v13, vcc
	s_waitcnt vmcnt(11)
	v_mov_b32_e32 v22, v244
	v_lshlrev_b32_e32 v24, 16, v22
	v_mul_f32_e32 v22, v24, v24
	s_nop 1
	v_mov_b32_dpp v22, v22 quad_perm:[1,0,3,2] row_mask:0xf bank_mask:0xf bound_ctrl:1
	v_fmac_f32_e32 v22, v24, v24
	s_nop 1
	v_add_f32_dpp v22, v22, v22 quad_perm:[2,3,0,1] row_mask:0xf bank_mask:0xf bound_ctrl:1
	s_nop 1
	v_add_f32_dpp v22, v22, v22 row_half_mirror row_mask:0xf bank_mask:0xf bound_ctrl:1
	s_nop 1
	v_add_f32_dpp v22, v22, v22 row_mirror row_mask:0xf bank_mask:0xf bound_ctrl:1
	s_nop 0
	v_readlane_b32 s6, v22, 16
	v_readlane_b32 s8, v22, 48
	v_readlane_b32 s4, v22, 0
	v_readlane_b32 s5, v22, 32
	v_mov_b32_e32 v22, s6
	v_mov_b32_e32 v23, s8
	v_pk_add_f32 v[22:23], s[4:5], v[22:23]
	s_mov_b32 s4, 0xf800000
	v_add_f32_e32 v22, v22, v23
	v_fmamk_f32 v22, v22, 0x3c800000, v252
	v_mul_f32_e32 v23, 0x4f800000, v22
	v_cmp_gt_f32_e32 vcc, s4, v22
	s_nop 1
	v_cndmask_b32_e32 v22, v22, v23, vcc
	v_sqrt_f32_e32 v23, v22
	s_nop 0
	v_add_u32_e32 v25, -1, v23
	v_add_u32_e32 v26, 1, v23
	v_fma_f32 v27, -v25, v23, v22
	v_fma_f32 v28, -v26, v23, v22
	v_cmp_ge_f32_e64 s[42:43], 0, v27
	s_nop 1
	v_cndmask_b32_e64 v23, v23, v25, s[42:43]
	v_cmp_lt_f32_e64 s[42:43], 0, v28
	s_nop 1
	v_cndmask_b32_e64 v23, v23, v26, s[42:43]
	v_mul_f32_e32 v25, 0x37800000, v23
	v_cndmask_b32_e32 v23, v23, v25, vcc
	v_mov_b32_e32 v25, 0x260
	v_cmp_class_f32_e32 vcc, v22, v25
	s_nop 1
	v_cndmask_b32_e32 v22, v23, v22, vcc
	v_div_scale_f32 v23, s[4:5], v22, v22, 1.0
	v_rcp_f32_e32 v25, v23
	v_div_scale_f32 v26, vcc, 1.0, v22, 1.0
	v_fma_f32 v27, -v23, v25, 1.0
	v_fmac_f32_e32 v25, v27, v25
	v_mul_f32_e32 v27, v26, v25
	v_fma_f32 v28, -v23, v27, v26
	v_fmac_f32_e32 v27, v28, v25
	v_fma_f32 v23, -v23, v27, v26
	v_div_fmas_f32 v23, v23, v25, v27
	v_div_fixup_f32 v22, v23, v22, 1.0
	v_mul_f32_e32 v22, v22, v24
	v_mul_f32_e32 v22, v17, v22
	ds_bpermute_b32 v23, v19, v22
	s_and_b64 vcc, exec, s[40:41]
	s_cbranch_vccnz .LBB0_412
	s_and_saveexec_b64 s[4:5], s[38:39]
	s_xor_b64 s[42:43], exec, s[4:5]
	s_cbranch_execz .LBB0_409
	v_mul_f32_e32 v22, v21, v22
	s_waitcnt lgkmcnt(0)
	v_fmac_f32_e32 v22, v20, v23

.LBB0_412:
	v_mul_f32_e32 v22, 0x3e38aa3b, v22
	s_waitcnt lgkmcnt(0)
	v_bfe_u32 v23, v22, 16, 1
	v_add3_u32 v24, v22, v23, s3
	v_add_co_u32_e32 v22, vcc, 0x2d200000, v14
	s_nop 1
	v_addc_co_u32_e32 v23, vcc, 0, v15, vcc
	global_store_short_d16_hi v[22:23], v24, off offset:512
	v_add_co_u32_e32 v22, vcc, 0x21400000, v12
	s_nop 1
	v_addc_co_u32_e32 v23, vcc, 0, v13, vcc
	s_waitcnt vmcnt(11)
	v_mov_b32_e32 v22, v245
	v_lshlrev_b32_e32 v24, 16, v22
	v_mul_f32_e32 v22, v24, v24
	s_nop 1
	v_mov_b32_dpp v22, v22 quad_perm:[1,0,3,2] row_mask:0xf bank_mask:0xf bound_ctrl:1
	v_fmac_f32_e32 v22, v24, v24
	s_nop 1
	v_add_f32_dpp v22, v22, v22 quad_perm:[2,3,0,1] row_mask:0xf bank_mask:0xf bound_ctrl:1
	s_nop 1
	v_add_f32_dpp v22, v22, v22 row_half_mirror row_mask:0xf bank_mask:0xf bound_ctrl:1
	s_nop 1
	v_add_f32_dpp v22, v22, v22 row_mirror row_mask:0xf bank_mask:0xf bound_ctrl:1
	s_nop 0
	v_readlane_b32 s6, v22, 16
	v_readlane_b32 s8, v22, 48
	v_readlane_b32 s4, v22, 0
	v_readlane_b32 s5, v22, 32
	v_mov_b32_e32 v22, s6
	v_mov_b32_e32 v23, s8
	v_pk_add_f32 v[22:23], s[4:5], v[22:23]
	s_mov_b32 s4, 0xf800000
	v_add_f32_e32 v22, v22, v23
	v_fmamk_f32 v22, v22, 0x3c800000, v252
	v_mul_f32_e32 v23, 0x4f800000, v22
	v_cmp_gt_f32_e32 vcc, s4, v22
	s_nop 1
	v_cndmask_b32_e32 v22, v22, v23, vcc
	v_sqrt_f32_e32 v23, v22
	s_nop 0
	v_add_u32_e32 v25, -1, v23
	v_add_u32_e32 v26, 1, v23
	v_fma_f32 v27, -v25, v23, v22
	v_fma_f32 v28, -v26, v23, v22
	v_cmp_ge_f32_e64 s[42:43], 0, v27
	s_nop 1
	v_cndmask_b32_e64 v23, v23, v25, s[42:43]
	v_cmp_lt_f32_e64 s[42:43], 0, v28
	s_nop 1
	v_cndmask_b32_e64 v23, v23, v26, s[42:43]
	v_mul_f32_e32 v25, 0x37800000, v23
	v_cndmask_b32_e32 v23, v23, v25, vcc
	v_mov_b32_e32 v25, 0x260
	v_cmp_class_f32_e32 vcc, v22, v25
	s_nop 1
	v_cndmask_b32_e32 v22, v23, v22, vcc
	v_div_scale_f32 v23, s[4:5], v22, v22, 1.0
	v_rcp_f32_e32 v25, v23
	v_div_scale_f32 v26, vcc, 1.0, v22, 1.0
	v_fma_f32 v27, -v23, v25, 1.0
	v_fmac_f32_e32 v25, v27, v25
	v_mul_f32_e32 v27, v26, v25
	v_fma_f32 v28, -v23, v27, v26
	v_fmac_f32_e32 v27, v28, v25
	v_fma_f32 v23, -v23, v27, v26
	v_div_fmas_f32 v23, v23, v25, v27
	v_div_fixup_f32 v22, v23, v22, 1.0
	v_mul_f32_e32 v22, v22, v24
	v_mul_f32_e32 v22, v17, v22
	ds_bpermute_b32 v23, v19, v22
	s_and_b64 vcc, exec, s[40:41]
	s_cbranch_vccnz .LBB0_418
	s_and_saveexec_b64 s[4:5], s[38:39]
	s_xor_b64 s[42:43], exec, s[4:5]
	s_cbranch_execz .LBB0_415
	v_mul_f32_e32 v22, v21, v22
	s_waitcnt lgkmcnt(0)
	v_fmac_f32_e32 v22, v20, v23

.LBB0_418:
	v_mul_f32_e32 v22, 0x3e38aa3b, v22
	s_waitcnt lgkmcnt(0)
	v_bfe_u32 v23, v22, 16, 1
	v_add3_u32 v24, v22, v23, s3
	v_add_co_u32_e32 v22, vcc, 0x2d200000, v14
	s_nop 1
	v_addc_co_u32_e32 v23, vcc, 0, v15, vcc
	global_store_short_d16_hi v[22:23], v24, off offset:640
	v_add_co_u32_e32 v22, vcc, 0x21400000, v12
	s_nop 1
	v_addc_co_u32_e32 v23, vcc, 0, v13, vcc
	s_waitcnt vmcnt(11)
	v_mov_b32_e32 v22, v246
	v_lshlrev_b32_e32 v24, 16, v22
	v_mul_f32_e32 v22, v24, v24
	s_nop 1
	v_mov_b32_dpp v22, v22 quad_perm:[1,0,3,2] row_mask:0xf bank_mask:0xf bound_ctrl:1
	v_fmac_f32_e32 v22, v24, v24
	s_nop 1
	v_add_f32_dpp v22, v22, v22 quad_perm:[2,3,0,1] row_mask:0xf bank_mask:0xf bound_ctrl:1
	s_nop 1
	v_add_f32_dpp v22, v22, v22 row_half_mirror row_mask:0xf bank_mask:0xf bound_ctrl:1
	s_nop 1
	v_add_f32_dpp v22, v22, v22 row_mirror row_mask:0xf bank_mask:0xf bound_ctrl:1
	s_nop 0
	v_readlane_b32 s6, v22, 16
	v_readlane_b32 s8, v22, 48
	v_readlane_b32 s4, v22, 0
	v_readlane_b32 s5, v22, 32
	v_mov_b32_e32 v22, s6
	v_mov_b32_e32 v23, s8
	v_pk_add_f32 v[22:23], s[4:5], v[22:23]
	s_mov_b32 s4, 0xf800000
	v_add_f32_e32 v22, v22, v23
	v_fmamk_f32 v22, v22, 0x3c800000, v252
	v_mul_f32_e32 v23, 0x4f800000, v22
	v_cmp_gt_f32_e32 vcc, s4, v22
	s_nop 1
	v_cndmask_b32_e32 v22, v22, v23, vcc
	v_sqrt_f32_e32 v23, v22
	s_nop 0
	v_add_u32_e32 v25, -1, v23
	v_add_u32_e32 v26, 1, v23
	v_fma_f32 v27, -v25, v23, v22
	v_fma_f32 v28, -v26, v23, v22
	v_cmp_ge_f32_e64 s[42:43], 0, v27
	s_nop 1
	v_cndmask_b32_e64 v23, v23, v25, s[42:43]
	v_cmp_lt_f32_e64 s[42:43], 0, v28
	s_nop 1
	v_cndmask_b32_e64 v23, v23, v26, s[42:43]
	v_mul_f32_e32 v25, 0x37800000, v23
	v_cndmask_b32_e32 v23, v23, v25, vcc
	v_mov_b32_e32 v25, 0x260
	v_cmp_class_f32_e32 vcc, v22, v25
	s_nop 1
	v_cndmask_b32_e32 v22, v23, v22, vcc
	v_div_scale_f32 v23, s[4:5], v22, v22, 1.0
	v_rcp_f32_e32 v25, v23
	v_div_scale_f32 v26, vcc, 1.0, v22, 1.0
	v_fma_f32 v27, -v23, v25, 1.0
	v_fmac_f32_e32 v25, v27, v25
	v_mul_f32_e32 v27, v26, v25
	v_fma_f32 v28, -v23, v27, v26
	v_fmac_f32_e32 v27, v28, v25
	v_fma_f32 v23, -v23, v27, v26
	v_div_fmas_f32 v23, v23, v25, v27
	v_div_fixup_f32 v22, v23, v22, 1.0
	v_mul_f32_e32 v22, v22, v24
	v_mul_f32_e32 v22, v17, v22
	ds_bpermute_b32 v23, v19, v22
	s_and_b64 vcc, exec, s[40:41]
	s_cbranch_vccnz .LBB0_424
	s_and_saveexec_b64 s[4:5], s[38:39]
	s_xor_b64 s[42:43], exec, s[4:5]
	s_cbranch_execz .LBB0_421
	v_mul_f32_e32 v22, v21, v22
	s_waitcnt lgkmcnt(0)
	v_fmac_f32_e32 v22, v20, v23

.LBB0_424:
	v_mul_f32_e32 v22, 0x3e38aa3b, v22
	s_waitcnt lgkmcnt(0)
	v_bfe_u32 v23, v22, 16, 1
	v_add3_u32 v24, v22, v23, s3
	v_add_co_u32_e32 v22, vcc, 0x2d200000, v14
	s_nop 1
	v_addc_co_u32_e32 v23, vcc, 0, v15, vcc
	global_store_short_d16_hi v[22:23], v24, off offset:768
	v_add_co_u32_e32 v22, vcc, 0x21400000, v12
	s_nop 1
	v_addc_co_u32_e32 v23, vcc, 0, v13, vcc
	s_waitcnt vmcnt(11)
	v_mov_b32_e32 v22, v247
	v_lshlrev_b32_e32 v24, 16, v22
	v_mul_f32_e32 v22, v24, v24
	s_nop 1
	v_mov_b32_dpp v22, v22 quad_perm:[1,0,3,2] row_mask:0xf bank_mask:0xf bound_ctrl:1
	v_fmac_f32_e32 v22, v24, v24
	s_nop 1
	v_add_f32_dpp v22, v22, v22 quad_perm:[2,3,0,1] row_mask:0xf bank_mask:0xf bound_ctrl:1
	s_nop 1
	v_add_f32_dpp v22, v22, v22 row_half_mirror row_mask:0xf bank_mask:0xf bound_ctrl:1
	s_nop 1
	v_add_f32_dpp v22, v22, v22 row_mirror row_mask:0xf bank_mask:0xf bound_ctrl:1
	s_nop 0
	v_readlane_b32 s6, v22, 16
	v_readlane_b32 s8, v22, 48
	v_readlane_b32 s4, v22, 0
	v_readlane_b32 s5, v22, 32
	v_mov_b32_e32 v22, s6
	v_mov_b32_e32 v23, s8
	v_pk_add_f32 v[22:23], s[4:5], v[22:23]
	s_mov_b32 s4, 0xf800000
	v_add_f32_e32 v22, v22, v23
	v_fmamk_f32 v22, v22, 0x3c800000, v252
	v_mul_f32_e32 v23, 0x4f800000, v22
	v_cmp_gt_f32_e32 vcc, s4, v22
	s_nop 1
	v_cndmask_b32_e32 v22, v22, v23, vcc
	v_sqrt_f32_e32 v23, v22
	s_nop 0
	v_add_u32_e32 v25, -1, v23
	v_add_u32_e32 v26, 1, v23
	v_fma_f32 v27, -v25, v23, v22
	v_fma_f32 v28, -v26, v23, v22
	v_cmp_ge_f32_e64 s[42:43], 0, v27
	s_nop 1
	v_cndmask_b32_e64 v23, v23, v25, s[42:43]
	v_cmp_lt_f32_e64 s[42:43], 0, v28
	s_nop 1
	v_cndmask_b32_e64 v23, v23, v26, s[42:43]
	v_mul_f32_e32 v25, 0x37800000, v23
	v_cndmask_b32_e32 v23, v23, v25, vcc
	v_mov_b32_e32 v25, 0x260
	v_cmp_class_f32_e32 vcc, v22, v25
	s_nop 1
	v_cndmask_b32_e32 v22, v23, v22, vcc
	v_div_scale_f32 v23, s[4:5], v22, v22, 1.0
	v_rcp_f32_e32 v25, v23
	v_div_scale_f32 v26, vcc, 1.0, v22, 1.0
	v_fma_f32 v27, -v23, v25, 1.0
	v_fmac_f32_e32 v25, v27, v25
	v_mul_f32_e32 v27, v26, v25
	v_fma_f32 v28, -v23, v27, v26
	v_fmac_f32_e32 v27, v28, v25
	v_fma_f32 v23, -v23, v27, v26
	v_div_fmas_f32 v23, v23, v25, v27
	v_div_fixup_f32 v22, v23, v22, 1.0
	v_mul_f32_e32 v22, v22, v24
	v_mul_f32_e32 v22, v17, v22
	ds_bpermute_b32 v23, v19, v22
	s_and_b64 vcc, exec, s[40:41]
	s_cbranch_vccnz .LBB0_430
	s_and_saveexec_b64 s[4:5], s[38:39]
	s_xor_b64 s[42:43], exec, s[4:5]
	s_cbranch_execz .LBB0_427
	v_mul_f32_e32 v22, v21, v22
	s_waitcnt lgkmcnt(0)
	v_fmac_f32_e32 v22, v20, v23

.LBB0_430:
	v_mul_f32_e32 v22, 0x3e38aa3b, v22
	s_waitcnt lgkmcnt(0)
	v_bfe_u32 v23, v22, 16, 1
	v_add_co_u32_e32 v14, vcc, 0x2d200000, v14
	v_add3_u32 v22, v22, v23, s3
	s_nop 0
	v_addc_co_u32_e32 v15, vcc, 0, v15, vcc
	global_store_short_d16_hi v[14:15], v22, off offset:896
	v_add_co_u32_e32 v14, vcc, 0x21401000, v12
	s_nop 1
	v_addc_co_u32_e32 v15, vcc, 0, v13, vcc
	s_waitcnt vmcnt(11)
	v_mov_b32_e32 v14, v248
	v_lshlrev_b32_e32 v22, 16, v14
	v_mul_f32_e32 v14, v22, v22
	s_nop 1
	v_mov_b32_dpp v14, v14 quad_perm:[1,0,3,2] row_mask:0xf bank_mask:0xf bound_ctrl:1
	v_fmac_f32_e32 v14, v22, v22
	s_nop 1
	v_add_f32_dpp v14, v14, v14 quad_perm:[2,3,0,1] row_mask:0xf bank_mask:0xf bound_ctrl:1
	s_nop 1
	v_add_f32_dpp v14, v14, v14 row_half_mirror row_mask:0xf bank_mask:0xf bound_ctrl:1
	s_nop 1
	v_add_f32_dpp v14, v14, v14 row_mirror row_mask:0xf bank_mask:0xf bound_ctrl:1
	s_nop 0
	v_readlane_b32 s6, v14, 16
	v_readlane_b32 s8, v14, 48
	v_readlane_b32 s4, v14, 0
	v_readlane_b32 s5, v14, 32
	v_mov_b32_e32 v14, s6
	v_mov_b32_e32 v15, s8
	v_pk_add_f32 v[14:15], s[4:5], v[14:15]
	s_mov_b32 s4, 0xf800000
	v_add_f32_e32 v14, v14, v15
	v_fmamk_f32 v14, v14, 0x3c800000, v252
	v_mul_f32_e32 v15, 0x4f800000, v14
	v_cmp_gt_f32_e32 vcc, s4, v14
	s_nop 1
	v_cndmask_b32_e32 v14, v14, v15, vcc
	v_sqrt_f32_e32 v15, v14
	s_nop 0
	v_add_u32_e32 v23, -1, v15
	v_add_u32_e32 v24, 1, v15
	v_fma_f32 v25, -v23, v15, v14
	v_fma_f32 v26, -v24, v15, v14
	v_cmp_ge_f32_e64 s[42:43], 0, v25
	s_nop 1
	v_cndmask_b32_e64 v15, v15, v23, s[42:43]
	v_cmp_lt_f32_e64 s[42:43], 0, v26
	s_nop 1
	v_cndmask_b32_e64 v15, v15, v24, s[42:43]
	v_mul_f32_e32 v23, 0x37800000, v15
	v_cndmask_b32_e32 v15, v15, v23, vcc
	v_mov_b32_e32 v23, 0x260
	v_cmp_class_f32_e32 vcc, v14, v23
	s_nop 1
	v_cndmask_b32_e32 v14, v15, v14, vcc
	v_div_scale_f32 v15, s[4:5], v14, v14, 1.0
	v_rcp_f32_e32 v23, v15
	v_div_scale_f32 v24, vcc, 1.0, v14, 1.0
	v_fma_f32 v25, -v15, v23, 1.0
	v_fmac_f32_e32 v23, v25, v23
	v_mul_f32_e32 v25, v24, v23
	v_fma_f32 v26, -v15, v25, v24
	v_fmac_f32_e32 v25, v26, v23
	v_fma_f32 v15, -v15, v25, v24
	v_div_fmas_f32 v15, v15, v23, v25
	v_div_fixup_f32 v14, v15, v14, 1.0
	v_mul_f32_e32 v14, v14, v22
	v_mul_f32_e32 v14, v16, v14
	ds_bpermute_b32 v15, v19, v14
	s_and_b64 vcc, exec, s[40:41]
	s_cbranch_vccnz .LBB0_436
	s_and_saveexec_b64 s[4:5], s[38:39]
	s_xor_b64 s[42:43], exec, s[4:5]
	s_cbranch_execz .LBB0_433
	v_mul_f32_e32 v14, v21, v14
	s_waitcnt lgkmcnt(0)
	v_fmac_f32_e32 v14, v20, v15

.LBB0_436:
	s_add_i32 s4, s48, 0xffffc000
	s_lshr_b32 s6, s4, 8
	s_ashr_i32 s8, s48, 13
	s_and_b64 s[4:5], s[56:57], exec
	s_cselect_b32 s6, s8, s6
	s_add_i32 s8, s2, 0x100
	s_and_b64 s[4:5], s[56:57], exec
	s_cselect_b32 s2, s8, s2
	s_mul_hi_i32 s4, s6, 0x2100
	s_mulk_i32 s6, 0x2100
	s_add_u32 s44, s6, s2
	s_addc_u32 s45, s4, 0
	s_lshl_b64 s[4:5], s[44:45], 8
	s_add_u32 s4, s74, s4
	s_addc_u32 s5, s75, s5
	s_waitcnt lgkmcnt(0)
	v_bfe_u32 v15, v14, 16, 1
	v_add3_u32 v24, v14, v15, s3
	v_lshl_add_u64 v[14:15], v[0:1], 1, s[4:5]
	s_mov_b32 s2, 0x2e300000
	v_add_co_u32_e32 v22, vcc, s2, v14
	s_nop 1
	v_addc_co_u32_e32 v23, vcc, 0, v15, vcc
	v_add_co_u32_e32 v12, vcc, s83, v12
	global_store_short_d16_hi v[22:23], v24, off
	s_nop 0
	v_addc_co_u32_e32 v13, vcc, 0, v13, vcc
	s_waitcnt vmcnt(11)
	v_mov_b32_e32 v12, v249
	v_lshlrev_b32_e32 v22, 16, v12
	v_mul_f32_e32 v12, v22, v22
	s_nop 1
	v_mov_b32_dpp v12, v12 quad_perm:[1,0,3,2] row_mask:0xf bank_mask:0xf bound_ctrl:1
	v_fmac_f32_e32 v12, v22, v22
	s_nop 1
	v_add_f32_dpp v12, v12, v12 quad_perm:[2,3,0,1] row_mask:0xf bank_mask:0xf bound_ctrl:1
	s_nop 1
	v_add_f32_dpp v12, v12, v12 row_half_mirror row_mask:0xf bank_mask:0xf bound_ctrl:1
	s_nop 1
	v_add_f32_dpp v12, v12, v12 row_mirror row_mask:0xf bank_mask:0xf bound_ctrl:1
	s_nop 0
	v_readlane_b32 s2, v12, 16
	v_readlane_b32 s6, v12, 48
	v_readlane_b32 s4, v12, 0
	v_readlane_b32 s5, v12, 32
	v_mov_b32_e32 v12, s2
	v_mov_b32_e32 v13, s6
	v_pk_add_f32 v[12:13], s[4:5], v[12:13]
	s_mov_b32 s2, 0xf800000
	v_add_f32_e32 v12, v12, v13
	v_fmamk_f32 v12, v12, 0x3c800000, v252
	v_mul_f32_e32 v13, 0x4f800000, v12
	v_cmp_gt_f32_e32 vcc, s2, v12
	s_nop 1
	v_cndmask_b32_e32 v12, v12, v13, vcc
	v_sqrt_f32_e32 v13, v12
	s_nop 0
	v_add_u32_e32 v23, -1, v13
	v_add_u32_e32 v24, 1, v13
	v_fma_f32 v25, -v23, v13, v12
	v_fma_f32 v26, -v24, v13, v12
	v_cmp_ge_f32_e64 s[42:43], 0, v25
	s_nop 1
	v_cndmask_b32_e64 v13, v13, v23, s[42:43]
	v_cmp_lt_f32_e64 s[42:43], 0, v26
	s_nop 1
	v_cndmask_b32_e64 v13, v13, v24, s[42:43]
	v_mul_f32_e32 v23, 0x37800000, v13
	v_cndmask_b32_e32 v13, v13, v23, vcc
	v_mov_b32_e32 v23, 0x260
	v_cmp_class_f32_e32 vcc, v12, v23
	s_nop 1
	v_cndmask_b32_e32 v12, v13, v12, vcc
	v_div_scale_f32 v13, s[4:5], v12, v12, 1.0
	v_rcp_f32_e32 v23, v13
	v_div_scale_f32 v24, vcc, 1.0, v12, 1.0
	v_fma_f32 v25, -v13, v23, 1.0
	v_fmac_f32_e32 v23, v25, v23
	v_mul_f32_e32 v25, v24, v23
	v_fma_f32 v26, -v13, v25, v24
	v_fmac_f32_e32 v25, v26, v23
	v_fma_f32 v13, -v13, v25, v24
	v_div_fmas_f32 v13, v13, v23, v25
	v_div_fixup_f32 v12, v13, v12, 1.0
	v_mul_f32_e32 v12, v12, v22
	v_mul_f32_e32 v12, v16, v12
	ds_bpermute_b32 v13, v19, v12
	s_and_b64 vcc, exec, s[40:41]
	s_cbranch_vccnz .LBB0_374
	s_and_saveexec_b64 s[4:5], s[38:39]
	s_xor_b64 s[40:41], exec, s[4:5]
	s_cbranch_execz .LBB0_439
	v_mul_f32_e32 v12, v21, v12
	s_waitcnt lgkmcnt(0)
	v_fmac_f32_e32 v12, v20, v13

.LBB0_447:
	s_mulk_i32 s6, 0xff7c
	s_add_i32 s6, s2, s6
	s_and_b64 s[10:11], s[42:43], exec
	s_cselect_b32 s6, s5, s6
	s_lshl_b32 s42, s6, 6
	v_add_u32_e32 v3, s42, v0
	s_movk_i32 s6, 0x100
	v_cmp_gt_i32_e32 vcc, s6, v3
	s_ashr_i32 s9, s40, s9
	v_mov_b32_e32 v8, 0xffffff00
	v_cndmask_b32_e64 v5, 13, 8, vcc
	v_mov_b32_e32 v9, 0x4000
	v_cndmask_b32_e32 v8, v8, v9, vcc
	v_lshlrev_b32_e64 v5, v5, s9
	v_add3_u32 v3, v8, v3, v5
	v_mov_b64_e32 v[8:9], s[36:37]
	s_and_b32 s10, s40, s8
	v_mad_i64_i32 v[8:9], s[8:9], v3, s17, v[8:9]
	s_lshl_b32 s24, s48, 1
	v_lshl_add_u64 v[8:9], v[8:9], 0, s[24:25]
	s_lshl_b32 s24, s10, 7
	v_lshl_add_u64 v[8:9], v[8:9], 0, s[24:25]
	global_load_dwordx4 v[116:119], v[8:9], off
	global_load_dwordx4 v[120:123], v[8:9], off offset:16
	global_load_dwordx4 v[124:127], v[8:9], off offset:32
	global_load_dwordx4 v[128:131], v[8:9], off offset:48
	global_load_dwordx4 v[132:135], v[8:9], off offset:64
	global_load_dwordx4 v[136:139], v[8:9], off offset:80
	global_load_dwordx4 v[140:143], v[8:9], off offset:96
	global_load_dwordx4 v[144:147], v[8:9], off offset:112
	s_waitcnt vmcnt(7)
	v_mov_b32_e32 v10, v116
	v_mov_b32_e32 v11, v117
	v_mov_b32_e32 v12, v118
	v_mov_b32_e32 v13, v119
	s_ashr_i32 s41, s40, 31
	s_mov_b64 s[48:49], -1
	s_and_b64 vcc, exec, s[44:45]
	ds_write_b16 v4, v10
	ds_write_b16_d16_hi v4, v10 offset:144
	ds_write_b16 v4, v11 offset:288
	ds_write_b16_d16_hi v4, v11 offset:432
	ds_write_b16 v4, v12 offset:576
	ds_write_b16_d16_hi v4, v12 offset:720
	ds_write_b16 v4, v13 offset:864
	ds_write_b16_d16_hi v4, v13 offset:1008
	s_waitcnt vmcnt(6)
	v_mov_b32_e32 v10, v120
	v_mov_b32_e32 v11, v121
	v_mov_b32_e32 v12, v122
	v_mov_b32_e32 v13, v123
	ds_write_b16 v4, v10 offset:1152
	ds_write_b16_d16_hi v4, v10 offset:1296
	ds_write_b16 v4, v11 offset:1440
	ds_write_b16_d16_hi v4, v11 offset:1584
	ds_write_b16 v4, v12 offset:1728
	ds_write_b16_d16_hi v4, v12 offset:1872
	ds_write_b16 v4, v13 offset:2016
	ds_write_b16_d16_hi v4, v13 offset:2160
	s_waitcnt vmcnt(5)
	v_mov_b32_e32 v10, v124
	v_mov_b32_e32 v11, v125
	v_mov_b32_e32 v12, v126
	v_mov_b32_e32 v13, v127
	ds_write_b16 v4, v10 offset:2304
	ds_write_b16_d16_hi v4, v10 offset:2448
	ds_write_b16 v4, v11 offset:2592
	ds_write_b16_d16_hi v4, v11 offset:2736
	ds_write_b16 v4, v12 offset:2880
	ds_write_b16_d16_hi v4, v12 offset:3024
	ds_write_b16 v4, v13 offset:3168
	ds_write_b16_d16_hi v4, v13 offset:3312
	s_waitcnt vmcnt(4)
	v_mov_b32_e32 v10, v128
	v_mov_b32_e32 v11, v129
	v_mov_b32_e32 v12, v130
	v_mov_b32_e32 v13, v131
	ds_write_b16 v4, v10 offset:3456
	ds_write_b16_d16_hi v4, v10 offset:3600
	ds_write_b16 v4, v11 offset:3744
	ds_write_b16_d16_hi v4, v11 offset:3888
	ds_write_b16 v4, v12 offset:4032
	ds_write_b16_d16_hi v4, v12 offset:4176
	ds_write_b16 v4, v13 offset:4320
	ds_write_b16_d16_hi v4, v13 offset:4464
	s_waitcnt vmcnt(3)
	v_mov_b32_e32 v10, v132
	v_mov_b32_e32 v11, v133
	v_mov_b32_e32 v12, v134
	v_mov_b32_e32 v13, v135
	ds_write_b16 v4, v10 offset:4608
	ds_write_b16_d16_hi v4, v10 offset:4752
	ds_write_b16 v4, v11 offset:4896
	ds_write_b16_d16_hi v4, v11 offset:5040
	ds_write_b16 v4, v12 offset:5184
	ds_write_b16_d16_hi v4, v12 offset:5328
	ds_write_b16 v4, v13 offset:5472
	ds_write_b16_d16_hi v4, v13 offset:5616
	s_waitcnt vmcnt(2)
	v_mov_b32_e32 v10, v136
	v_mov_b32_e32 v11, v137
	v_mov_b32_e32 v12, v138
	v_mov_b32_e32 v13, v139
	ds_write_b16 v4, v10 offset:5760
	ds_write_b16_d16_hi v4, v10 offset:5904
	ds_write_b16 v4, v11 offset:6048
	ds_write_b16_d16_hi v4, v11 offset:6192
	ds_write_b16 v4, v12 offset:6336
	ds_write_b16_d16_hi v4, v12 offset:6480
	ds_write_b16 v4, v13 offset:6624
	ds_write_b16_d16_hi v4, v13 offset:6768
	s_waitcnt vmcnt(1)
	v_mov_b32_e32 v10, v140
	v_mov_b32_e32 v11, v141
	v_mov_b32_e32 v12, v142
	v_mov_b32_e32 v13, v143
	ds_write_b16 v4, v10 offset:6912
	ds_write_b16_d16_hi v4, v10 offset:7056
	ds_write_b16 v4, v11 offset:7200
	ds_write_b16_d16_hi v4, v11 offset:7344
	ds_write_b16 v4, v12 offset:7488
	ds_write_b16_d16_hi v4, v12 offset:7632
	ds_write_b16 v4, v13 offset:7776
	ds_write_b16_d16_hi v4, v13 offset:7920
	s_waitcnt vmcnt(0)
	v_mov_b32_e32 v8, v144
	v_mov_b32_e32 v9, v145
	v_mov_b32_e32 v10, v146
	v_mov_b32_e32 v11, v147
	ds_write_b16 v4, v8 offset:8064
	ds_write_b16_d16_hi v4, v8 offset:8208
	ds_write_b16 v4, v9 offset:8352
	ds_write_b16_d16_hi v4, v9 offset:8496
	ds_write_b16 v4, v10 offset:8640
	ds_write_b16_d16_hi v4, v10 offset:8784
	ds_write_b16 v4, v11 offset:8928
	ds_write_b16_d16_hi v4, v11 offset:9072
	s_waitcnt lgkmcnt(0)
	s_cbranch_vccz .LBB0_449
	s_lshl_b64 s[8:9], s[40:41], 6
	v_lshl_add_u64 v[10:11], s[8:9], 0, v[0:1]
	v_mov_b64_e32 v[8:9], s[38:39]
	s_movk_i32 s6, 0x4200
	v_mad_u64_u32 v[8:9], s[8:9], v10, s6, v[8:9]
	v_mad_i32_i24 v9, v11, s6, v9
	s_mov_b64 s[48:49], 0

.LBB0_1828:
	v_readlane_b32 s0, v253, 4
	v_readlane_b32 s1, v253, 5
	s_mov_b64 s[4:5], s[0:1]
	s_cmp_lt_i32 s4, 52
	v_readlane_b32 s2, v253, 6
	v_readlane_b32 s3, v253, 7
	s_cselect_b64 s[0:1], -1, 0
	s_cmp_gt_i32 s5, 51
	s_cselect_b64 s[2:3], -1, 0
	s_and_b64 s[0:1], s[0:1], s[2:3]
	s_and_b64 vcc, exec, s[0:1]
	s_cbranch_vccz .LBB0_1832
	v_readlane_b32 s0, v253, 0
	v_readlane_b32 s1, v253, 1
	s_load_dwordx2 s[6:7], s[0:1], 0x100
	s_waitcnt lgkmcnt(0)
	s_load_dwordx2 s[0:1], s[0:1], 0x108
	s_waitcnt lgkmcnt(0)
	s_lshl_b32 s2, s92, 3
	s_add_i32 s2, s2, s93
	s_cmpk_gt_i32 s2, 0x3fff
	v_mbcnt_lo_u32_b32 v0, -1, 0
	v_mbcnt_hi_u32_b32 v0, -1, v0
	s_cbranch_scc1 .LBB0_1832
	v_lshlrev_b32_e32 v2, 2, v0
	v_ashrrev_i32_e32 v3, 31, v2
	s_waitcnt vmcnt(0)
	v_lshl_add_u64 v[16:17], v[2:3], 2, s[6:7]
	s_mov_b64 s[6:7], 0x1000
	v_lshl_add_u64 v[18:19], v[16:17], 0, s[6:7]
	s_mov_b64 s[6:7], 0x1400
	v_lshl_add_u64 v[20:21], v[16:17], 0, s[6:7]
	s_mov_b64 s[6:7], 0x1800
	s_ashr_i32 s3, s2, 31
	s_lshl_b32 s4, s77, 3
	v_lshl_add_u64 v[22:23], v[16:17], 0, s[6:7]
	s_mov_b64 s[6:7], 0x1c00
	s_lshl_b64 s[10:11], s[2:3], 13
	v_lshl_add_u64 v[24:25], v[16:17], 0, s[6:7]
	s_add_u32 s6, s0, s10
	s_addc_u32 s7, s1, s11
	s_ashr_i32 s5, s4, 31
	s_lshl_b64 s[8:9], s[4:5], 13
	s_waitcnt lgkmcnt(0)
	v_ashrrev_i32_e32 v1, 31, v0
	s_add_u32 s10, s74, s10
	v_lshlrev_b64 v[26:27], 4, v[0:1]
	s_addc_u32 s11, s75, s11
	s_mov_b32 s3, 0x19001000
	v_mov_b32_e32 v28, 0x358637bd
	s_mov_b32 s5, 0xf800000
	v_mov_b32_e32 v29, 0x260
	s_movk_i32 s12, 0x1000
	global_load_dwordx4 v[100:103], v[16:17], off
	global_load_dwordx4 v[104:107], v[16:17], off offset:1024
	global_load_dwordx4 v[108:111], v[16:17], off offset:2048
	global_load_dwordx4 v[112:115], v[16:17], off offset:3072
	global_load_dwordx4 v[116:119], v[18:19], off
	global_load_dwordx4 v[120:123], v[20:21], off
	global_load_dwordx4 v[124:127], v[22:23], off
	global_load_dwordx4 v[128:131], v[24:25], off
	s_waitcnt vmcnt(0)
.LBB0_1831:
	s_nop 0
	v_lshl_add_u64 v[0:1], s[10:11], 0, v[26:27]
	v_add_co_u32_e64 v48, s[0:1], s3, v0
	v_add_co_u32_e32 v46, vcc, 0x19000000, v0
	s_nop 0
	v_addc_co_u32_e64 v49, s[0:1], 0, v1, s[0:1]
	v_addc_co_u32_e32 v47, vcc, 0, v1, vcc
	global_load_dwordx4 v[4:7], v[48:49], off
	global_load_dwordx4 v[12:15], v[48:49], off offset:1024
	global_load_dwordx4 v[8:11], v[48:49], off offset:2048
	global_load_dwordx4 v[30:33], v[46:47], off
	global_load_dwordx4 v[34:37], v[46:47], off offset:1024
	global_load_dwordx4 v[38:41], v[46:47], off offset:2048
	global_load_dwordx4 v[42:45], v[46:47], off offset:3072
	global_load_dwordx4 v[0:3], v[48:49], off offset:3072
	v_lshl_add_u64 v[50:51], s[6:7], 0, v[26:27]
	v_mov_b32_e32 v46, v100
	v_mov_b32_e32 v47, v101
	v_mov_b32_e32 v48, v102
	v_mov_b32_e32 v49, v103
	s_add_i32 s2, s2, s4
	s_add_u32 s6, s6, s8
	s_addc_u32 s7, s7, s9
	s_add_u32 s10, s10, s8
	s_addc_u32 s11, s11, s9
	s_cmpk_lt_i32 s2, 0x4000
	s_waitcnt vmcnt(7)
	v_mul_f32_e32 v75, v4, v4
	s_waitcnt vmcnt(6)
	v_pk_mul_f32 v[52:53], v[14:15], v[14:15]
	v_pk_mul_f32 v[54:55], v[12:13], v[12:13]
	s_waitcnt vmcnt(5)
	v_mul_f32_e32 v56, v9, v9
	v_mul_f32_e32 v58, v11, v11
	s_waitcnt vmcnt(4)
	v_mov_b32_e32 v62, v31
	s_waitcnt vmcnt(3)
	v_mov_b32_e32 v63, v35
	v_mov_b32_e32 v66, v33
	v_mov_b32_e32 v67, v37
	s_waitcnt vmcnt(0)
	v_mul_f32_e32 v83, v2, v2
	v_mul_f32_e32 v84, v3, v3
	v_mov_b32_e32 v60, v30
	v_mov_b32_e32 v61, v34
	v_mov_b32_e32 v64, v32
	v_mov_b32_e32 v65, v36
	v_pk_mul_f32 v[68:69], v[40:41], v[40:41]
	v_pk_mul_f32 v[70:71], v[38:39], v[38:39]
	v_pk_mov_b32 v[76:77], v[54:55], v[52:53] op_sel:[1,0]
	v_mov_b32_e32 v55, v53
	v_pk_fma_f32 v[52:53], v[8:9], v[8:9], v[56:57] op_sel_hi:[1,1,0]
	v_pk_fma_f32 v[56:57], v[10:11], v[10:11], v[58:59] op_sel_hi:[1,1,0]
	v_pk_mul_f32 v[58:59], v[62:63], v[62:63]
	v_pk_mul_f32 v[62:63], v[66:67], v[66:67]
	v_pk_mov_b32 v[66:67], v[70:71], v[68:69] op_sel:[1,0]
	v_mov_b32_e32 v71, v69
	v_mov_b32_e32 v53, v83
	v_mov_b32_e32 v57, v84
	v_pk_fma_f32 v[58:59], v[60:61], v[60:61], v[58:59]
	v_pk_fma_f32 v[60:61], v[64:65], v[64:65], v[62:63]
	v_mul_f32_e32 v72, v43, v43
	v_mul_f32_e32 v74, v45, v45
	v_pk_add_f32 v[62:63], v[66:67], v[70:71]
	v_pk_add_f32 v[52:53], v[52:53], v[56:57]
	v_pk_add_f32 v[56:57], v[58:59], v[60:61]
	v_mul_f32_e32 v78, v5, v5
	v_mul_f32_e32 v79, v6, v6
	v_mul_f32_e32 v80, v7, v7
	v_pk_fma_f32 v[68:69], v[42:43], v[42:43], v[72:73] op_sel_hi:[1,1,0]
	v_pk_fma_f32 v[72:73], v[44:45], v[44:45], v[74:75] op_sel_hi:[1,1,0]
	v_pk_add_f32 v[58:59], v[62:63], v[62:63] op_sel:[0,1] op_sel_hi:[1,0]
	v_pk_add_f32 v[56:57], v[56:57], v[56:57] op_sel:[0,1] op_sel_hi:[1,0]
	v_mov_b32_e32 v69, v79
	v_mov_b32_e32 v73, v80
	v_mov_b32_e32 v59, v78
	v_mov_b32_e32 v57, v75
	v_pk_add_f32 v[60:61], v[68:69], v[72:73]
	v_pk_add_f32 v[56:57], v[56:57], v[58:59]
	v_pk_add_f32 v[54:55], v[76:77], v[54:55]
	v_pk_add_f32 v[56:57], v[56:57], v[60:61]
	v_mul_f32_e32 v81, v0, v0
	v_mul_f32_e32 v82, v1, v1
	v_pk_add_f32 v[54:55], v[54:55], v[54:55] op_sel:[0,1] op_sel_hi:[1,0]
	v_pk_add_f32 v[56:57], v[56:57], v[56:57] op_sel:[0,1] op_sel_hi:[1,0]
	v_mov_b32_e32 v55, v82
	v_mov_b32_e32 v57, v81
	v_pk_add_f32 v[54:55], v[56:57], v[54:55]
	s_nop 0
	v_pk_add_f32 v[52:53], v[54:55], v[52:53]
	s_nop 0
	v_add_f32_e32 v52, v52, v53
	s_nop 1
	v_add_f32_dpp v52, v52, v52 quad_perm:[1,0,3,2] row_mask:0xf bank_mask:0xf bound_ctrl:1
	s_nop 1
	v_add_f32_dpp v52, v52, v52 quad_perm:[2,3,0,1] row_mask:0xf bank_mask:0xf bound_ctrl:1
	s_nop 1
	v_add_f32_dpp v52, v52, v52 row_half_mirror row_mask:0xf bank_mask:0xf bound_ctrl:1
	s_nop 1
	v_add_f32_dpp v52, v52, v52 row_mirror row_mask:0xf bank_mask:0xf bound_ctrl:1
	s_nop 0
	v_readlane_b32 s13, v52, 16
	v_readlane_b32 s14, v52, 48
	v_readlane_b32 s0, v52, 0
	v_readlane_b32 s1, v52, 32
	v_mov_b32_e32 v52, s13
	v_mov_b32_e32 v53, s14
	v_pk_add_f32 v[52:53], s[0:1], v[52:53]
	s_nop 0
	v_add_f32_e32 v52, v52, v53
	v_fmamk_f32 v52, v52, 0x3a000000, v28
	v_mul_f32_e32 v53, 0x4f800000, v52
	v_cmp_gt_f32_e32 vcc, s5, v52
	s_nop 1
	v_cndmask_b32_e32 v52, v52, v53, vcc
	v_sqrt_f32_e32 v53, v52
	s_nop 0
	v_add_u32_e32 v54, -1, v53
	v_add_u32_e32 v55, 1, v53
	v_fma_f32 v56, -v54, v53, v52
	v_fma_f32 v57, -v55, v53, v52
	v_cmp_ge_f32_e64 s[0:1], 0, v56
	s_nop 1
	v_cndmask_b32_e64 v53, v53, v54, s[0:1]
	v_cmp_lt_f32_e64 s[0:1], 0, v57
	s_nop 1
	v_cndmask_b32_e64 v53, v53, v55, s[0:1]
	v_mul_f32_e32 v54, 0x37800000, v53
	v_cndmask_b32_e32 v53, v53, v54, vcc
	v_cmp_class_f32_e32 vcc, v52, v29
	s_nop 1
	v_cndmask_b32_e32 v52, v53, v52, vcc
	v_div_scale_f32 v53, s[0:1], v52, v52, 1.0
	v_rcp_f32_e32 v55, v53
	v_div_scale_f32 v54, vcc, 1.0, v52, 1.0
	v_fma_f32 v56, -v53, v55, 1.0
	v_fmac_f32_e32 v55, v56, v55
	v_mul_f32_e32 v56, v54, v55
	v_fma_f32 v57, -v53, v56, v54
	v_fmac_f32_e32 v56, v57, v55
	v_fma_f32 v53, -v53, v56, v54
	v_div_fmas_f32 v53, v53, v55, v56
	v_div_fixup_f32 v52, v53, v52, 1.0
	v_pk_mul_f32 v[30:31], v[30:31], v[52:53] op_sel_hi:[1,0]
	v_pk_mul_f32 v[32:33], v[32:33], v[52:53] op_sel_hi:[1,0]
	v_pk_mul_f32 v[30:31], v[46:47], v[30:31]
	v_pk_mul_f32 v[32:33], v[48:49], v[32:33]
	global_store_dwordx4 v[50:51], v[30:33], off
	s_nop 1
	v_mov_b32_e32 v30, v104
	v_mov_b32_e32 v31, v105
	v_mov_b32_e32 v32, v106
	v_mov_b32_e32 v33, v107
	v_pk_mul_f32 v[36:37], v[36:37], v[52:53] op_sel_hi:[1,0]
	v_pk_mul_f32 v[34:35], v[34:35], v[52:53] op_sel_hi:[1,0]
	v_pk_mul_f32 v[6:7], v[6:7], v[52:53] op_sel_hi:[1,0]
	v_pk_mul_f32 v[4:5], v[4:5], v[52:53] op_sel_hi:[1,0]
	v_pk_mul_f32 v[14:15], v[14:15], v[52:53] op_sel_hi:[1,0]
	v_pk_mul_f32 v[12:13], v[12:13], v[52:53] op_sel_hi:[1,0]
	v_pk_mul_f32 v[10:11], v[10:11], v[52:53] op_sel_hi:[1,0]
	v_pk_mul_f32 v[8:9], v[8:9], v[52:53] op_sel_hi:[1,0]
	v_pk_mul_f32 v[2:3], v[2:3], v[52:53] op_sel_hi:[1,0]
	v_pk_mul_f32 v[0:1], v[0:1], v[52:53] op_sel_hi:[1,0]
	v_pk_mul_f32 v[30:31], v[30:31], v[34:35]
	v_pk_mul_f32 v[32:33], v[32:33], v[36:37]
	global_store_dwordx4 v[50:51], v[30:33], off offset:1024
	s_nop 1
	v_mov_b32_e32 v30, v108
	v_mov_b32_e32 v31, v109
	v_mov_b32_e32 v32, v110
	v_mov_b32_e32 v33, v111
	v_pk_mul_f32 v[34:35], v[40:41], v[52:53] op_sel_hi:[1,0]
	v_pk_mul_f32 v[36:37], v[38:39], v[52:53] op_sel_hi:[1,0]
	v_pk_mul_f32 v[32:33], v[32:33], v[34:35]
	v_pk_mul_f32 v[30:31], v[30:31], v[36:37]
	global_store_dwordx4 v[50:51], v[30:33], off offset:2048
	s_nop 1
	v_mov_b32_e32 v30, v112
	v_mov_b32_e32 v31, v113
	v_mov_b32_e32 v32, v114
	v_mov_b32_e32 v33, v115
	v_pk_mul_f32 v[34:35], v[44:45], v[52:53] op_sel_hi:[1,0]
	v_pk_mul_f32 v[36:37], v[42:43], v[52:53] op_sel_hi:[1,0]
	v_pk_mul_f32 v[32:33], v[32:33], v[34:35]
	v_pk_mul_f32 v[30:31], v[30:31], v[36:37]
	global_store_dwordx4 v[50:51], v[30:33], off offset:3072
	s_nop 1
	v_mov_b32_e32 v30, v116
	v_mov_b32_e32 v31, v117
	v_mov_b32_e32 v32, v118
	v_mov_b32_e32 v33, v119
	v_add_co_u32_e32 v34, vcc, s12, v50
	v_pk_mul_f32 v[4:5], v[30:31], v[4:5]
	v_addc_co_u32_e32 v35, vcc, 0, v51, vcc
	v_pk_mul_f32 v[6:7], v[32:33], v[6:7]
	global_store_dwordx4 v[34:35], v[4:7], off
	s_nop 1
	v_mov_b32_e32 v4, v120
	v_mov_b32_e32 v5, v121
	v_mov_b32_e32 v6, v122
	v_mov_b32_e32 v7, v123
	v_pk_mul_f32 v[4:5], v[12:13], v[4:5]
	v_pk_mul_f32 v[6:7], v[14:15], v[6:7]
	global_store_dwordx4 v[34:35], v[4:7], off offset:1024
	s_nop 1
	v_mov_b32_e32 v4, v124
	v_mov_b32_e32 v5, v125
	v_mov_b32_e32 v6, v126
	v_mov_b32_e32 v7, v127
	v_pk_mul_f32 v[4:5], v[8:9], v[4:5]
	v_pk_mul_f32 v[6:7], v[10:11], v[6:7]
	global_store_dwordx4 v[34:35], v[4:7], off offset:2048
	s_nop 1
	v_mov_b32_e32 v4, v128
	v_mov_b32_e32 v5, v129
	v_mov_b32_e32 v6, v130
	v_mov_b32_e32 v7, v131
	v_pk_mul_f32 v[0:1], v[0:1], v[4:5]
	v_pk_mul_f32 v[2:3], v[2:3], v[6:7]
	global_store_dwordx4 v[34:35], v[0:3], off offset:3072
	s_cbranch_scc1 .LBB0_1831
